# on v65: P6 gMLP affine rows loaded a group ahead (rotating register sets), P9 stage A LDS loads issued ahead of stage B (renamed registers)
# speedup vs baseline: 1.0033x; 1.0033x over previous
; __device__ __forceinline__ float gelu_t(float x) { return x * sigm(1.5957691216057308f * (x + 0.044715f * x * x * x)); }
; __global__ void __launch_bounds__(512, 2) fwd_megakernel(Params p) {
;     ...
;                 for (int tk = gw; tk < NB * 32 * 2 * 16; tk += NGW) {
;                     const int g = tk & 15, hh = (tk >> 4) & 1, bn = tk >> 5;
;                     const int q = hh * 64 + lane; const size_t m = (size_t)bn * 128 + q;
;                     const f16_t* src = P + m * INW + RIN + RW + g * 64;
;                     float v[64]; float s = 0.f;
; #pragma unroll
;                     for (int i = 0; i < 8; ++i) { float f[8]; h8_to_f(*(const u32x4*)(src + i * 8), f);
; #pragma unroll
;                         for (int j = 0; j < 8; ++j) { v[i * 8 + j] = gelu_t(f[j]); s += v[i * 8 + j]; } }
.LBB0_574:
	s_ashr_i32 s0, s35, 5
	s_ashr_i32 s1, s0, 31
	v_and_or_b32 v0, s16, 64, v240
	s_lshl_b64 s[6:7], s[0:1], 7
	s_and_b32 s24, s35, 15
	v_lshlrev_b32_e32 v66, 1, v0
	v_or_b32_e32 v0, s6, v0
	s_lshl_b32 s2, s24, 7
	s_lshl_b64 s[0:1], s[0:1], 18
	v_mad_u64_u32 v[0:1], s[36:37], v0, s20, v[64:65]
	s_add_u32 s0, s8, s0
	v_mad_i32_i24 v1, s7, v74, v1
	s_addc_u32 s1, s9, s1
	s_lshl_b32 s6, s24, 14
	v_lshl_add_u64 v[0:1], v[0:1], 0, s[2:3]
	s_add_u32 s6, s0, s6
	v_add_co_u32_e32 v58, vcc, s21, v0
	s_addc_u32 s7, s1, 0
	s_lshl_b32 s0, s24, 8
	v_lshl_add_u64 v[56:57], v[0:1], 0, s[4:5]
	v_addc_co_u32_e32 v59, vcc, 0, v1, vcc
	v_mov_b32_e32 v77, s0
	global_load_dwordx4 v[52:55], v[56:57], off offset:16
	global_load_dwordx4 v[48:51], v[56:57], off offset:32
	global_load_dwordx4 v[44:47], v[56:57], off offset:48
	global_load_dwordx4 v[40:43], v[56:57], off offset:64
	global_load_dwordx4 v[36:39], v[56:57], off offset:80
	global_load_dwordx4 v[32:35], v[56:57], off offset:96
	global_load_dwordx4 v[8:11], v77, s[12:13] offset:48
	global_load_dwordx4 v[0:3], v77, s[14:15] offset:48
	global_load_dwordx4 v[20:23], v77, s[12:13] offset:32
	global_load_dwordx4 v[4:7], v77, s[14:15] offset:32
	global_load_dwordx4 v[24:27], v77, s[12:13] offset:16
	global_load_dwordx4 v[12:15], v77, s[14:15] offset:16
	global_load_dwordx4 v[28:31], v77, s[12:13]
	global_load_dwordx4 v[16:19], v77, s[14:15]
	global_load_dwordx4 v[200:203], v77, s[12:13] offset:64
	global_load_dwordx4 v[204:207], v77, s[14:15] offset:64
	global_load_dwordx4 v[208:211], v77, s[12:13] offset:80
	global_load_dwordx4 v[212:215], v77, s[14:15] offset:80
	global_load_dwordx4 v[216:219], v77, s[12:13] offset:96
	global_load_dwordx4 v[220:223], v77, s[14:15] offset:96
	global_load_dwordx4 v[224:227], v77, s[12:13] offset:112
	global_load_dwordx4 v[228:231], v77, s[14:15] offset:112
	global_load_dwordx4 v[60:63], v[58:59], off offset:512
	s_nop 0
	global_load_dwordx4 v[56:59], v[56:57], off offset:112
	v_lshl_add_u64 v[68:69], s[6:7], 0, v[66:67]
	v_add_co_u32_e32 v72, vcc, s23, v68
	s_add_i32 s35, s35, s30
	s_nop 0
	v_addc_co_u32_e32 v73, vcc, 0, v69, vcc
	v_add_co_u32_e32 v70, vcc, s21, v68
	s_add_i32 s16, s16, s17
	s_nop 0
	v_addc_co_u32_e32 v71, vcc, 0, v69, vcc
	s_cmpk_lt_i32 s35, 0x2000
	s_waitcnt vmcnt(0)
	v_cvt_f32_f16_e32 v110, v36
	v_cvt_f32_f16_sdwa v111, v36 dst_sel:DWORD dst_unused:UNUSED_PAD src0_sel:WORD_1
	v_cvt_f32_f16_e32 v112, v37
	v_cvt_f32_f16_sdwa v113, v37 dst_sel:DWORD dst_unused:UNUSED_PAD src0_sel:WORD_1
	v_cvt_f32_f16_e32 v114, v38
	v_cvt_f32_f16_e32 v78, v52
	v_cvt_f32_f16_sdwa v79, v52 dst_sel:DWORD dst_unused:UNUSED_PAD src0_sel:WORD_1
	v_cvt_f32_f16_e32 v80, v53
	v_cvt_f32_f16_sdwa v81, v53 dst_sel:DWORD dst_unused:UNUSED_PAD src0_sel:WORD_1
	v_cvt_f32_f16_e32 v126, v60
	v_cvt_f32_f16_sdwa v127, v60 dst_sel:DWORD dst_unused:UNUSED_PAD src0_sel:WORD_1
	v_cvt_f32_f16_e32 v128, v61
	v_cvt_f32_f16_sdwa v129, v61 dst_sel:DWORD dst_unused:UNUSED_PAD src0_sel:WORD_1
	v_cvt_f32_f16_e32 v130, v62
	v_mul_f32_e32 v191, 0x3d372713, v126
	v_cvt_f32_f16_sdwa v131, v62 dst_sel:DWORD dst_unused:UNUSED_PAD src0_sel:WORD_1
	v_mul_f32_e32 v192, 0x3d372713, v127
	v_mul_f32_e32 v126, v191, v126
	v_cvt_f32_f16_e32 v132, v63
	v_mul_f32_e32 v193, 0x3d372713, v128
	v_mul_f32_e32 v127, v192, v127
	v_fma_mix_f32 v126, v126, v60, v60 op_sel_hi:[0,1,1]
	v_cvt_f32_f16_sdwa v133, v63 dst_sel:DWORD dst_unused:UNUSED_PAD src0_sel:WORD_1
	v_mul_f32_e32 v194, 0x3d372713, v129
	v_mul_f32_e32 v128, v193, v128
	v_fma_mix_f32 v127, v127, v60, v60 op_sel:[0,1,1] op_sel_hi:[0,1,1]
	v_mul_f32_e32 v126, 0x3fcc422a, v126
	v_mul_f32_e32 v195, 0x3d372713, v130
	v_mul_f32_e32 v129, v194, v129
	v_fma_mix_f32 v128, v128, v61, v61 op_sel_hi:[0,1,1]
	v_mul_f32_e32 v127, 0x3fcc422a, v127
	v_mul_f32_e32 v126, 0xbfb8aa3b, v126
	v_mul_f32_e32 v196, 0x3d372713, v131
	v_mul_f32_e32 v130, v195, v130
	v_fma_mix_f32 v129, v129, v61, v61 op_sel:[0,1,1] op_sel_hi:[0,1,1]
	v_mul_f32_e32 v128, 0x3fcc422a, v128
	v_mul_f32_e32 v127, 0xbfb8aa3b, v127
	v_exp_f32_e32 v126, v126
	v_mul_f32_e32 v197, 0x3d372713, v132
	v_mul_f32_e32 v131, v196, v131
	v_fma_mix_f32 v130, v130, v62, v62 op_sel_hi:[0,1,1]
	v_mul_f32_e32 v129, 0x3fcc422a, v129
	v_mul_f32_e32 v128, 0xbfb8aa3b, v128
	v_exp_f32_e32 v127, v127
	v_mul_f32_e32 v198, 0x3d372713, v133
	v_mul_f32_e32 v132, v197, v132
	v_fma_mix_f32 v131, v131, v62, v62 op_sel:[0,1,1] op_sel_hi:[0,1,1]
	v_mul_f32_e32 v130, 0x3fcc422a, v130
	v_mul_f32_e32 v129, 0xbfb8aa3b, v129
	v_exp_f32_e32 v128, v128
	v_cvt_f32_f16_e32 v82, v54
	v_mul_f32_e32 v142, 0x3d372713, v78
	v_mul_f32_e32 v133, v198, v133
	v_fma_mix_f32 v132, v132, v63, v63 op_sel_hi:[0,1,1]
	v_mul_f32_e32 v131, 0x3fcc422a, v131
	v_mul_f32_e32 v130, 0xbfb8aa3b, v130
	v_exp_f32_e32 v129, v129
	v_cvt_f32_f16_sdwa v83, v54 dst_sel:DWORD dst_unused:UNUSED_PAD src0_sel:WORD_1
	v_cvt_f32_f16_e32 v134, v56
	v_mul_f32_e32 v143, 0x3d372713, v79
	v_mul_f32_e32 v78, v142, v78
	v_fma_mix_f32 v133, v133, v63, v63 op_sel:[0,1,1] op_sel_hi:[0,1,1]
	v_mul_f32_e32 v132, 0x3fcc422a, v132
	v_mul_f32_e32 v131, 0xbfb8aa3b, v131
	v_exp_f32_e32 v130, v130
	v_add_f32_e32 v126, 1.0, v126
	v_cvt_f32_f16_e32 v84, v55
	v_mul_f32_e32 v144, 0x3d372713, v80
	v_mul_f32_e32 v79, v143, v79
	v_fma_mix_f32 v78, v78, v52, v52 op_sel_hi:[0,1,1]
	v_mul_f32_e32 v133, 0x3fcc422a, v133
	v_mul_f32_e32 v132, 0xbfb8aa3b, v132
	v_exp_f32_e32 v131, v131
	v_add_f32_e32 v127, 1.0, v127
	v_rcp_f32_e32 v126, v126
	v_cvt_f32_f16_sdwa v85, v55 dst_sel:DWORD dst_unused:UNUSED_PAD src0_sel:WORD_1
	v_mul_f32_e32 v145, 0x3d372713, v81
	v_mul_f32_e32 v80, v144, v80
; __device__ __forceinline__ float gelu_t(float x) { return x * sigm(1.5957691216057308f * (x + 0.044715f * x * x * x)); }
; __global__ void __launch_bounds__(512, 2) fwd_megakernel(Params p) {
;     ...
;                     for (int i = 0; i < 8; ++i) { float f[8]; h8_to_f(*(const u32x4*)(src + i * 8), f);
; #pragma unroll
;                         for (int j = 0; j < 8; ++j) { v[i * 8 + j] = gelu_t(f[j]); s += v[i * 8 + j]; } }
	v_fma_mix_f32 v79, v79, v52, v52 op_sel:[0,1,1] op_sel_hi:[0,1,1]
	v_mul_f32_e32 v78, 0x3fcc422a, v78
	v_mul_f32_e32 v133, 0xbfb8aa3b, v133
	v_exp_f32_e32 v132, v132
	v_add_f32_e32 v128, 1.0, v128
	v_rcp_f32_e32 v127, v127
	v_cvt_f32_f16_e32 v86, v48
	v_mul_f32_e32 v146, 0x3d372713, v82
	v_mul_f32_e32 v81, v145, v81
	v_fma_mix_f32 v80, v80, v53, v53 op_sel_hi:[0,1,1]
	v_mul_f32_e32 v79, 0x3fcc422a, v79
	v_mul_f32_e32 v78, 0xbfb8aa3b, v78
	v_exp_f32_e32 v133, v133
	v_add_f32_e32 v129, 1.0, v129
	v_rcp_f32_e32 v128, v128
	v_cvt_f32_f16_sdwa v87, v48 dst_sel:DWORD dst_unused:UNUSED_PAD src0_sel:WORD_1
	v_mul_f32_e32 v147, 0x3d372713, v83
	v_mul_f32_e32 v82, v146, v82
	v_mul_f32_e32 v142, 0x3d372713, v134
	v_fma_mix_f32 v81, v81, v53, v53 op_sel:[0,1,1] op_sel_hi:[0,1,1]
	v_mul_f32_e32 v80, 0x3fcc422a, v80
	v_mul_f32_e32 v79, 0xbfb8aa3b, v79
	v_exp_f32_e32 v78, v78
	v_add_f32_e32 v130, 1.0, v130
	v_rcp_f32_e32 v129, v129
	v_cvt_f32_f16_e32 v88, v49
	v_mul_f32_e32 v148, 0x3d372713, v84
	v_mul_f32_e32 v83, v147, v83
	v_fma_mix_f32 v82, v82, v54, v54 op_sel_hi:[0,1,1]
	v_mul_f32_e32 v134, v142, v134
	v_mul_f32_e32 v81, 0x3fcc422a, v81
	v_mul_f32_e32 v80, 0xbfb8aa3b, v80
	v_exp_f32_e32 v79, v79
	v_add_f32_e32 v131, 1.0, v131
	v_rcp_f32_e32 v130, v130
	v_fma_mix_f32 v142, v126, v60, 0 op_sel_hi:[0,1,0]
	v_cvt_f32_f16_sdwa v89, v49 dst_sel:DWORD dst_unused:UNUSED_PAD src0_sel:WORD_1
	v_mul_f32_e32 v149, 0x3d372713, v85
	v_mul_f32_e32 v84, v148, v84
	v_fma_mix_f32 v83, v83, v54, v54 op_sel:[0,1,1] op_sel_hi:[0,1,1]
	v_mul_f32_e32 v82, 0x3fcc422a, v82
	v_mul_f32_e32 v81, 0xbfb8aa3b, v81
	v_exp_f32_e32 v80, v80
	v_add_f32_e32 v132, 1.0, v132
	v_rcp_f32_e32 v131, v131
	v_fma_mix_f32 v142, v127, v60, v142 op_sel:[0,1,0] op_sel_hi:[0,1,0]
	v_cvt_f32_f16_e32 v90, v50
	v_mul_f32_e32 v150, 0x3d372713, v86
	v_mul_f32_e32 v85, v149, v85
	v_fma_mix_f32 v84, v84, v55, v55 op_sel_hi:[0,1,1]
	v_mul_f32_e32 v83, 0x3fcc422a, v83
	v_mul_f32_e32 v82, 0xbfb8aa3b, v82
	v_exp_f32_e32 v81, v81
	v_add_f32_e32 v133, 1.0, v133
	v_rcp_f32_e32 v132, v132
	v_fma_mix_f32 v142, v128, v61, v142 op_sel_hi:[0,1,0]
	v_cvt_f32_f16_sdwa v91, v50 dst_sel:DWORD dst_unused:UNUSED_PAD src0_sel:WORD_1
	v_mul_f32_e32 v151, 0x3d372713, v87
	v_mul_f32_e32 v86, v150, v86
	v_fma_mix_f32 v85, v85, v55, v55 op_sel:[0,1,1] op_sel_hi:[0,1,1]
	v_mul_f32_e32 v84, 0x3fcc422a, v84
	v_mul_f32_e32 v83, 0xbfb8aa3b, v83
	v_exp_f32_e32 v82, v82
	v_add_f32_e32 v78, 1.0, v78
	v_rcp_f32_e32 v133, v133
	v_fma_mix_f32 v142, v129, v61, v142 op_sel:[0,1,0] op_sel_hi:[0,1,0]
	v_cvt_f32_f16_e32 v92, v51
	v_mul_f32_e32 v152, 0x3d372713, v88
	v_mul_f32_e32 v87, v151, v87
	v_fma_mix_f32 v86, v86, v48, v48 op_sel_hi:[0,1,1]
	v_mul_f32_e32 v85, 0x3fcc422a, v85
	v_mul_f32_e32 v84, 0xbfb8aa3b, v84
	v_exp_f32_e32 v83, v83
	v_add_f32_e32 v79, 1.0, v79
	v_rcp_f32_e32 v78, v78
	v_fma_mix_f32 v142, v130, v62, v142 op_sel_hi:[0,1,0]
	v_cvt_f32_f16_sdwa v93, v51 dst_sel:DWORD dst_unused:UNUSED_PAD src0_sel:WORD_1
	v_mul_f32_e32 v153, 0x3d372713, v89
	v_mul_f32_e32 v88, v152, v88
	v_fma_mix_f32 v87, v87, v48, v48 op_sel:[0,1,1] op_sel_hi:[0,1,1]
	v_mul_f32_e32 v86, 0x3fcc422a, v86
	v_mul_f32_e32 v85, 0xbfb8aa3b, v85
	v_exp_f32_e32 v84, v84
	v_add_f32_e32 v80, 1.0, v80
	v_rcp_f32_e32 v79, v79
	v_fma_mix_f32 v142, v131, v62, v142 op_sel:[0,1,0] op_sel_hi:[0,1,0]
	v_cvt_f32_f16_e32 v94, v44
	v_mul_f32_e32 v154, 0x3d372713, v90
	v_mul_f32_e32 v89, v153, v89
	v_fma_mix_f32 v88, v88, v49, v49 op_sel_hi:[0,1,1]
	v_mul_f32_e32 v87, 0x3fcc422a, v87
	v_mul_f32_e32 v86, 0xbfb8aa3b, v86
	v_exp_f32_e32 v85, v85
	v_add_f32_e32 v81, 1.0, v81
	v_rcp_f32_e32 v80, v80
	v_fma_mix_f32 v142, v132, v63, v142 op_sel_hi:[0,1,0]
	v_cvt_f32_f16_sdwa v95, v44 dst_sel:DWORD dst_unused:UNUSED_PAD src0_sel:WORD_1
	v_mul_f32_e32 v155, 0x3d372713, v91
	v_mul_f32_e32 v90, v154, v90
	v_fma_mix_f32 v89, v89, v49, v49 op_sel:[0,1,1] op_sel_hi:[0,1,1]
	v_mul_f32_e32 v88, 0x3fcc422a, v88
	v_mul_f32_e32 v87, 0xbfb8aa3b, v87
	v_exp_f32_e32 v86, v86
	v_add_f32_e32 v82, 1.0, v82
	v_rcp_f32_e32 v81, v81
	v_fma_mix_f32 v142, v133, v63, v142 op_sel:[0,1,0] op_sel_hi:[0,1,0]
	v_cvt_f32_f16_e32 v96, v45
	v_mul_f32_e32 v156, 0x3d372713, v92
	v_mul_f32_e32 v91, v155, v91
	v_fma_mix_f32 v90, v90, v50, v50 op_sel_hi:[0,1,1]
	v_mul_f32_e32 v89, 0x3fcc422a, v89
	v_mul_f32_e32 v88, 0xbfb8aa3b, v88
	v_exp_f32_e32 v87, v87
	v_add_f32_e32 v83, 1.0, v83
	v_rcp_f32_e32 v82, v82
	v_fma_mix_f32 v142, v78, v52, v142 op_sel_hi:[0,1,0]
	v_cvt_f32_f16_sdwa v97, v45 dst_sel:DWORD dst_unused:UNUSED_PAD src0_sel:WORD_1
	v_mul_f32_e32 v157, 0x3d372713, v93
	v_mul_f32_e32 v92, v156, v92
	v_fma_mix_f32 v91, v91, v50, v50 op_sel:[0,1,1] op_sel_hi:[0,1,1]
	v_mul_f32_e32 v90, 0x3fcc422a, v90
	v_mul_f32_e32 v89, 0xbfb8aa3b, v89
	v_exp_f32_e32 v88, v88
	v_add_f32_e32 v84, 1.0, v84
	v_rcp_f32_e32 v83, v83
	v_fma_mix_f32 v142, v79, v52, v142 op_sel:[0,1,0] op_sel_hi:[0,1,0]
	v_cvt_f32_f16_e32 v98, v46
	v_mul_f32_e32 v158, 0x3d372713, v94
	v_mul_f32_e32 v93, v157, v93
	v_fma_mix_f32 v92, v92, v51, v51 op_sel_hi:[0,1,1]
	v_mul_f32_e32 v91, 0x3fcc422a, v91
	v_mul_f32_e32 v90, 0xbfb8aa3b, v90
	v_exp_f32_e32 v89, v89
	v_add_f32_e32 v85, 1.0, v85
	v_rcp_f32_e32 v84, v84
	v_fma_mix_f32 v142, v80, v53, v142 op_sel_hi:[0,1,0]
	v_cvt_f32_f16_sdwa v99, v46 dst_sel:DWORD dst_unused:UNUSED_PAD src0_sel:WORD_1
	v_mul_f32_e32 v159, 0x3d372713, v95
	v_mul_f32_e32 v94, v158, v94
	v_fma_mix_f32 v93, v93, v51, v51 op_sel:[0,1,1] op_sel_hi:[0,1,1]
	v_mul_f32_e32 v92, 0x3fcc422a, v92
	v_mul_f32_e32 v91, 0xbfb8aa3b, v91
	v_exp_f32_e32 v90, v90
	v_add_f32_e32 v86, 1.0, v86
	v_rcp_f32_e32 v85, v85
; __device__ __forceinline__ float gelu_t(float x) { return x * sigm(1.5957691216057308f * (x + 0.044715f * x * x * x)); }
; __global__ void __launch_bounds__(512, 2) fwd_megakernel(Params p) {
;     ...
;                     for (int i = 0; i < 8; ++i) { float f[8]; h8_to_f(*(const u32x4*)(src + i * 8), f);
; #pragma unroll
;                         for (int j = 0; j < 8; ++j) { v[i * 8 + j] = gelu_t(f[j]); s += v[i * 8 + j]; } }
	v_fma_mix_f32 v142, v81, v53, v142 op_sel:[0,1,0] op_sel_hi:[0,1,0]
	v_cvt_f32_f16_e32 v100, v47
	v_mul_f32_e32 v160, 0x3d372713, v96
	v_mul_f32_e32 v95, v159, v95
	v_fma_mix_f32 v94, v94, v44, v44 op_sel_hi:[0,1,1]
	v_mul_f32_e32 v93, 0x3fcc422a, v93
	v_mul_f32_e32 v92, 0xbfb8aa3b, v92
	v_exp_f32_e32 v91, v91
	v_add_f32_e32 v87, 1.0, v87
	v_rcp_f32_e32 v86, v86
	v_fma_mix_f32 v142, v82, v54, v142 op_sel_hi:[0,1,0]
	v_cvt_f32_f16_sdwa v101, v47 dst_sel:DWORD dst_unused:UNUSED_PAD src0_sel:WORD_1
	v_mul_f32_e32 v161, 0x3d372713, v97
	v_mul_f32_e32 v96, v160, v96
	v_fma_mix_f32 v95, v95, v44, v44 op_sel:[0,1,1] op_sel_hi:[0,1,1]
	v_mul_f32_e32 v94, 0x3fcc422a, v94
	v_mul_f32_e32 v93, 0xbfb8aa3b, v93
	v_exp_f32_e32 v92, v92
	v_add_f32_e32 v88, 1.0, v88
	v_rcp_f32_e32 v87, v87
	v_fma_mix_f32 v142, v83, v54, v142 op_sel:[0,1,0] op_sel_hi:[0,1,0]
	v_cvt_f32_f16_e32 v102, v40
	v_mul_f32_e32 v162, 0x3d372713, v98
	v_mul_f32_e32 v97, v161, v97
	v_fma_mix_f32 v96, v96, v45, v45 op_sel_hi:[0,1,1]
	v_mul_f32_e32 v95, 0x3fcc422a, v95
	v_mul_f32_e32 v94, 0xbfb8aa3b, v94
	v_exp_f32_e32 v93, v93
	v_add_f32_e32 v89, 1.0, v89
	v_rcp_f32_e32 v88, v88
	v_fma_mix_f32 v142, v84, v55, v142 op_sel_hi:[0,1,0]
	v_cvt_f32_f16_sdwa v103, v40 dst_sel:DWORD dst_unused:UNUSED_PAD src0_sel:WORD_1
	v_mul_f32_e32 v163, 0x3d372713, v99
	v_mul_f32_e32 v98, v162, v98
	v_fma_mix_f32 v97, v97, v45, v45 op_sel:[0,1,1] op_sel_hi:[0,1,1]
	v_mul_f32_e32 v96, 0x3fcc422a, v96
	v_mul_f32_e32 v95, 0xbfb8aa3b, v95
	v_exp_f32_e32 v94, v94
	v_add_f32_e32 v90, 1.0, v90
	v_rcp_f32_e32 v89, v89
	v_fma_mix_f32 v142, v85, v55, v142 op_sel:[0,1,0] op_sel_hi:[0,1,0]
	v_cvt_f32_f16_e32 v104, v41
	v_mul_f32_e32 v164, 0x3d372713, v100
	v_mul_f32_e32 v99, v163, v99
	v_fma_mix_f32 v98, v98, v46, v46 op_sel_hi:[0,1,1]
	v_mul_f32_e32 v97, 0x3fcc422a, v97
	v_mul_f32_e32 v96, 0xbfb8aa3b, v96
	v_exp_f32_e32 v95, v95
	v_add_f32_e32 v91, 1.0, v91
	v_rcp_f32_e32 v90, v90
	v_fma_mix_f32 v142, v86, v48, v142 op_sel_hi:[0,1,0]
	v_cvt_f32_f16_sdwa v105, v41 dst_sel:DWORD dst_unused:UNUSED_PAD src0_sel:WORD_1
	v_mul_f32_e32 v165, 0x3d372713, v101
	v_mul_f32_e32 v100, v164, v100
	v_fma_mix_f32 v99, v99, v46, v46 op_sel:[0,1,1] op_sel_hi:[0,1,1]
	v_mul_f32_e32 v98, 0x3fcc422a, v98
	v_mul_f32_e32 v97, 0xbfb8aa3b, v97
	v_exp_f32_e32 v96, v96
	v_add_f32_e32 v92, 1.0, v92
	v_rcp_f32_e32 v91, v91
	v_fma_mix_f32 v142, v87, v48, v142 op_sel:[0,1,0] op_sel_hi:[0,1,0]
	v_cvt_f32_f16_e32 v106, v42
	v_mul_f32_e32 v166, 0x3d372713, v102
	v_mul_f32_e32 v101, v165, v101
	v_fma_mix_f32 v100, v100, v47, v47 op_sel_hi:[0,1,1]
	v_mul_f32_e32 v99, 0x3fcc422a, v99
	v_mul_f32_e32 v98, 0xbfb8aa3b, v98
	v_exp_f32_e32 v97, v97
	v_add_f32_e32 v93, 1.0, v93
	v_rcp_f32_e32 v92, v92
	v_fma_mix_f32 v142, v88, v49, v142 op_sel_hi:[0,1,0]
	v_cvt_f32_f16_sdwa v107, v42 dst_sel:DWORD dst_unused:UNUSED_PAD src0_sel:WORD_1
	v_mul_f32_e32 v167, 0x3d372713, v103
	v_mul_f32_e32 v102, v166, v102
	v_fma_mix_f32 v101, v101, v47, v47 op_sel:[0,1,1] op_sel_hi:[0,1,1]
	v_mul_f32_e32 v100, 0x3fcc422a, v100
	v_mul_f32_e32 v99, 0xbfb8aa3b, v99
	v_exp_f32_e32 v98, v98
	v_add_f32_e32 v94, 1.0, v94
	v_rcp_f32_e32 v93, v93
	v_fma_mix_f32 v142, v89, v49, v142 op_sel:[0,1,0] op_sel_hi:[0,1,0]
	v_cvt_f32_f16_e32 v108, v43
	v_mul_f32_e32 v168, 0x3d372713, v104
	v_mul_f32_e32 v103, v167, v103
	v_fma_mix_f32 v102, v102, v40, v40 op_sel_hi:[0,1,1]
	v_mul_f32_e32 v101, 0x3fcc422a, v101
	v_mul_f32_e32 v100, 0xbfb8aa3b, v100
	v_exp_f32_e32 v99, v99
	v_add_f32_e32 v95, 1.0, v95
	v_rcp_f32_e32 v94, v94
	v_fma_mix_f32 v142, v90, v50, v142 op_sel_hi:[0,1,0]
	v_cvt_f32_f16_sdwa v109, v43 dst_sel:DWORD dst_unused:UNUSED_PAD src0_sel:WORD_1
	v_mul_f32_e32 v169, 0x3d372713, v105
	v_mul_f32_e32 v104, v168, v104
	v_fma_mix_f32 v103, v103, v40, v40 op_sel:[0,1,1] op_sel_hi:[0,1,1]
	v_mul_f32_e32 v102, 0x3fcc422a, v102
	v_mul_f32_e32 v101, 0xbfb8aa3b, v101
	v_exp_f32_e32 v100, v100
	v_add_f32_e32 v96, 1.0, v96
	v_rcp_f32_e32 v95, v95
	v_fma_mix_f32 v142, v91, v50, v142 op_sel:[0,1,0] op_sel_hi:[0,1,0]
	v_mul_f32_e32 v170, 0x3d372713, v106
	v_mul_f32_e32 v105, v169, v105
	v_fma_mix_f32 v104, v104, v41, v41 op_sel_hi:[0,1,1]
	v_mul_f32_e32 v103, 0x3fcc422a, v103
	v_mul_f32_e32 v102, 0xbfb8aa3b, v102
	v_exp_f32_e32 v101, v101
	v_add_f32_e32 v97, 1.0, v97
	v_rcp_f32_e32 v96, v96
	v_fma_mix_f32 v142, v92, v51, v142 op_sel_hi:[0,1,0]
	v_mul_f32_e32 v171, 0x3d372713, v107
	v_mul_f32_e32 v106, v170, v106
	v_fma_mix_f32 v105, v105, v41, v41 op_sel:[0,1,1] op_sel_hi:[0,1,1]
	v_mul_f32_e32 v104, 0x3fcc422a, v104
	v_mul_f32_e32 v103, 0xbfb8aa3b, v103
	v_exp_f32_e32 v102, v102
	v_add_f32_e32 v98, 1.0, v98
	v_rcp_f32_e32 v97, v97
	v_fma_mix_f32 v142, v93, v51, v142 op_sel:[0,1,0] op_sel_hi:[0,1,0]
	v_mul_f32_e32 v172, 0x3d372713, v108
	v_mul_f32_e32 v107, v171, v107
	v_fma_mix_f32 v106, v106, v42, v42 op_sel_hi:[0,1,1]
	v_mul_f32_e32 v105, 0x3fcc422a, v105
	v_mul_f32_e32 v104, 0xbfb8aa3b, v104
	v_exp_f32_e32 v103, v103
	v_add_f32_e32 v99, 1.0, v99
	v_rcp_f32_e32 v98, v98
	v_fma_mix_f32 v142, v94, v44, v142 op_sel_hi:[0,1,0]
	v_mul_f32_e32 v173, 0x3d372713, v109
	v_mul_f32_e32 v108, v172, v108
	v_fma_mix_f32 v107, v107, v42, v42 op_sel:[0,1,1] op_sel_hi:[0,1,1]
	v_mul_f32_e32 v106, 0x3fcc422a, v106
	v_mul_f32_e32 v105, 0xbfb8aa3b, v105
	v_exp_f32_e32 v104, v104
	v_add_f32_e32 v100, 1.0, v100
	v_rcp_f32_e32 v99, v99
	v_fma_mix_f32 v142, v95, v44, v142 op_sel:[0,1,0] op_sel_hi:[0,1,0]
	v_mul_f32_e32 v174, 0x3d372713, v110
	v_mul_f32_e32 v109, v173, v109
	v_fma_mix_f32 v108, v108, v43, v43 op_sel_hi:[0,1,1]
	v_mul_f32_e32 v107, 0x3fcc422a, v107
	v_mul_f32_e32 v106, 0xbfb8aa3b, v106
	v_exp_f32_e32 v105, v105
; __device__ __forceinline__ float gelu_t(float x) { return x * sigm(1.5957691216057308f * (x + 0.044715f * x * x * x)); }
; __global__ void __launch_bounds__(512, 2) fwd_megakernel(Params p) {
;     ...
;                     for (int i = 0; i < 8; ++i) { float f[8]; h8_to_f(*(const u32x4*)(src + i * 8), f);
; #pragma unroll
;                         for (int j = 0; j < 8; ++j) { v[i * 8 + j] = gelu_t(f[j]); s += v[i * 8 + j]; } }
	v_add_f32_e32 v101, 1.0, v101
	v_rcp_f32_e32 v100, v100
	v_fma_mix_f32 v142, v96, v45, v142 op_sel_hi:[0,1,0]
	v_cvt_f32_f16_sdwa v115, v38 dst_sel:DWORD dst_unused:UNUSED_PAD src0_sel:WORD_1
	v_mul_f32_e32 v175, 0x3d372713, v111
	v_mul_f32_e32 v110, v174, v110
	v_fma_mix_f32 v109, v109, v43, v43 op_sel:[0,1,1] op_sel_hi:[0,1,1]
	v_mul_f32_e32 v108, 0x3fcc422a, v108
	v_mul_f32_e32 v107, 0xbfb8aa3b, v107
	v_exp_f32_e32 v106, v106
	v_add_f32_e32 v102, 1.0, v102
	v_rcp_f32_e32 v101, v101
	v_fma_mix_f32 v142, v97, v45, v142 op_sel:[0,1,0] op_sel_hi:[0,1,0]
	v_cvt_f32_f16_e32 v116, v39
	v_mul_f32_e32 v176, 0x3d372713, v112
	v_mul_f32_e32 v111, v175, v111
	v_fma_mix_f32 v110, v110, v36, v36 op_sel_hi:[0,1,1]
	v_mul_f32_e32 v109, 0x3fcc422a, v109
	v_mul_f32_e32 v108, 0xbfb8aa3b, v108
	v_exp_f32_e32 v107, v107
	v_add_f32_e32 v103, 1.0, v103
	v_rcp_f32_e32 v102, v102
	v_fma_mix_f32 v142, v98, v46, v142 op_sel_hi:[0,1,0]
	v_cvt_f32_f16_sdwa v117, v39 dst_sel:DWORD dst_unused:UNUSED_PAD src0_sel:WORD_1
	v_mul_f32_e32 v177, 0x3d372713, v113
	v_mul_f32_e32 v112, v176, v112
	v_fma_mix_f32 v111, v111, v36, v36 op_sel:[0,1,1] op_sel_hi:[0,1,1]
	v_mul_f32_e32 v110, 0x3fcc422a, v110
	v_mul_f32_e32 v109, 0xbfb8aa3b, v109
	v_exp_f32_e32 v108, v108
	v_add_f32_e32 v104, 1.0, v104
	v_rcp_f32_e32 v103, v103
	v_fma_mix_f32 v142, v99, v46, v142 op_sel:[0,1,0] op_sel_hi:[0,1,0]
	v_cvt_f32_f16_e32 v118, v32
	v_mul_f32_e32 v178, 0x3d372713, v114
	v_mul_f32_e32 v113, v177, v113
	v_fma_mix_f32 v112, v112, v37, v37 op_sel_hi:[0,1,1]
	v_mul_f32_e32 v111, 0x3fcc422a, v111
	v_mul_f32_e32 v110, 0xbfb8aa3b, v110
	v_exp_f32_e32 v109, v109
	v_add_f32_e32 v105, 1.0, v105
	v_rcp_f32_e32 v104, v104
	v_fma_mix_f32 v142, v100, v47, v142 op_sel_hi:[0,1,0]
	v_cvt_f32_f16_sdwa v119, v32 dst_sel:DWORD dst_unused:UNUSED_PAD src0_sel:WORD_1
	v_mul_f32_e32 v179, 0x3d372713, v115
	v_mul_f32_e32 v114, v178, v114
	v_fma_mix_f32 v113, v113, v37, v37 op_sel:[0,1,1] op_sel_hi:[0,1,1]
	v_mul_f32_e32 v112, 0x3fcc422a, v112
	v_mul_f32_e32 v111, 0xbfb8aa3b, v111
	v_exp_f32_e32 v110, v110
	v_add_f32_e32 v106, 1.0, v106
	v_rcp_f32_e32 v105, v105
	v_fma_mix_f32 v142, v101, v47, v142 op_sel:[0,1,0] op_sel_hi:[0,1,0]
	v_cvt_f32_f16_e32 v120, v33
	v_mul_f32_e32 v181, 0x3d372713, v116
	v_mul_f32_e32 v115, v179, v115
	v_fma_mix_f32 v114, v114, v38, v38 op_sel_hi:[0,1,1]
	v_mul_f32_e32 v113, 0x3fcc422a, v113
	v_mul_f32_e32 v112, 0xbfb8aa3b, v112
	v_exp_f32_e32 v111, v111
	v_add_f32_e32 v107, 1.0, v107
	v_rcp_f32_e32 v106, v106
	v_fma_mix_f32 v142, v102, v40, v142 op_sel_hi:[0,1,0]
	v_cvt_f32_f16_sdwa v121, v33 dst_sel:DWORD dst_unused:UNUSED_PAD src0_sel:WORD_1
	v_mul_f32_e32 v182, 0x3d372713, v117
	v_mul_f32_e32 v116, v181, v116
	v_fma_mix_f32 v115, v115, v38, v38 op_sel:[0,1,1] op_sel_hi:[0,1,1]
	v_mul_f32_e32 v114, 0x3fcc422a, v114
	v_mul_f32_e32 v113, 0xbfb8aa3b, v113
	v_exp_f32_e32 v112, v112
	v_add_f32_e32 v108, 1.0, v108
	v_rcp_f32_e32 v107, v107
	v_fma_mix_f32 v142, v103, v40, v142 op_sel:[0,1,0] op_sel_hi:[0,1,0]
	v_cvt_f32_f16_e32 v122, v34
	v_mul_f32_e32 v183, 0x3d372713, v118
	v_mul_f32_e32 v117, v182, v117
	v_fma_mix_f32 v116, v116, v39, v39 op_sel_hi:[0,1,1]
	v_mul_f32_e32 v115, 0x3fcc422a, v115
	v_mul_f32_e32 v114, 0xbfb8aa3b, v114
	v_exp_f32_e32 v113, v113
	v_add_f32_e32 v109, 1.0, v109
	v_rcp_f32_e32 v108, v108
	v_fma_mix_f32 v142, v104, v41, v142 op_sel_hi:[0,1,0]
	v_cvt_f32_f16_sdwa v123, v34 dst_sel:DWORD dst_unused:UNUSED_PAD src0_sel:WORD_1
	v_mul_f32_e32 v184, 0x3d372713, v119
	v_mul_f32_e32 v118, v183, v118
	v_fma_mix_f32 v117, v117, v39, v39 op_sel:[0,1,1] op_sel_hi:[0,1,1]
	v_mul_f32_e32 v116, 0x3fcc422a, v116
	v_mul_f32_e32 v115, 0xbfb8aa3b, v115
	v_exp_f32_e32 v114, v114
	v_add_f32_e32 v110, 1.0, v110
	v_rcp_f32_e32 v109, v109
	v_fma_mix_f32 v142, v105, v41, v142 op_sel:[0,1,0] op_sel_hi:[0,1,0]
	v_cvt_f32_f16_e32 v124, v35
	v_mul_f32_e32 v185, 0x3d372713, v120
	v_mul_f32_e32 v119, v184, v119
	v_fma_mix_f32 v118, v118, v32, v32 op_sel_hi:[0,1,1]
	v_mul_f32_e32 v117, 0x3fcc422a, v117
	v_mul_f32_e32 v116, 0xbfb8aa3b, v116
	v_exp_f32_e32 v115, v115
	v_add_f32_e32 v111, 1.0, v111
	v_rcp_f32_e32 v110, v110
	v_fma_mix_f32 v142, v106, v42, v142 op_sel_hi:[0,1,0]
	v_cvt_f32_f16_sdwa v125, v35 dst_sel:DWORD dst_unused:UNUSED_PAD src0_sel:WORD_1
	v_mul_f32_e32 v186, 0x3d372713, v121
	v_mul_f32_e32 v120, v185, v120
	v_fma_mix_f32 v119, v119, v32, v32 op_sel:[0,1,1] op_sel_hi:[0,1,1]
	v_mul_f32_e32 v118, 0x3fcc422a, v118
	v_mul_f32_e32 v117, 0xbfb8aa3b, v117
	v_exp_f32_e32 v116, v116
	v_add_f32_e32 v112, 1.0, v112
	v_rcp_f32_e32 v111, v111
	v_fma_mix_f32 v142, v107, v42, v142 op_sel:[0,1,0] op_sel_hi:[0,1,0]
	v_mul_f32_e32 v187, 0x3d372713, v122
	v_mul_f32_e32 v121, v186, v121
	v_fma_mix_f32 v120, v120, v33, v33 op_sel_hi:[0,1,1]
	v_mul_f32_e32 v119, 0x3fcc422a, v119
	v_mul_f32_e32 v118, 0xbfb8aa3b, v118
	v_exp_f32_e32 v117, v117
	v_add_f32_e32 v113, 1.0, v113
	v_rcp_f32_e32 v112, v112
	v_fma_mix_f32 v142, v108, v43, v142 op_sel_hi:[0,1,0]
	v_cvt_f32_f16_sdwa v135, v56 dst_sel:DWORD dst_unused:UNUSED_PAD src0_sel:WORD_1
	v_mul_f32_e32 v188, 0x3d372713, v123
	v_mul_f32_e32 v122, v187, v122
	v_fma_mix_f32 v121, v121, v33, v33 op_sel:[0,1,1] op_sel_hi:[0,1,1]
	v_mul_f32_e32 v120, 0x3fcc422a, v120
	v_mul_f32_e32 v119, 0xbfb8aa3b, v119
	v_exp_f32_e32 v118, v118
	v_add_f32_e32 v114, 1.0, v114
	v_rcp_f32_e32 v113, v113
	v_fma_mix_f32 v142, v109, v43, v142 op_sel:[0,1,0] op_sel_hi:[0,1,0]
	v_cvt_f32_f16_e32 v136, v57
	v_mul_f32_e32 v189, 0x3d372713, v124
	v_mul_f32_e32 v123, v188, v123
	v_fma_mix_f32 v122, v122, v34, v34 op_sel_hi:[0,1,1]
	v_mul_f32_e32 v121, 0x3fcc422a, v121
; __device__ __forceinline__ float gelu_t(float x) { return x * sigm(1.5957691216057308f * (x + 0.044715f * x * x * x)); }
; __global__ void __launch_bounds__(512, 2) fwd_megakernel(Params p) {
;     ...
;                     for (int i = 0; i < 8; ++i) { float f[8]; h8_to_f(*(const u32x4*)(src + i * 8), f);
; #pragma unroll
;                         for (int j = 0; j < 8; ++j) { v[i * 8 + j] = gelu_t(f[j]); s += v[i * 8 + j]; } }
;                     const float mean = s * (1.0f / 64.0f); float s2 = 0.f;
; #pragma unroll
;                     for (int d = 0; d < 64; ++d) { v[d] -= mean; s2 += v[d] * v[d]; }
	v_mul_f32_e32 v120, 0xbfb8aa3b, v120
	v_exp_f32_e32 v119, v119
	v_add_f32_e32 v115, 1.0, v115
	v_rcp_f32_e32 v114, v114
	v_fma_mix_f32 v142, v110, v36, v142 op_sel_hi:[0,1,0]
	v_cvt_f32_f16_sdwa v137, v57 dst_sel:DWORD dst_unused:UNUSED_PAD src0_sel:WORD_1
	v_mul_f32_e32 v190, 0x3d372713, v125
	v_mul_f32_e32 v124, v189, v124
	v_fma_mix_f32 v123, v123, v34, v34 op_sel:[0,1,1] op_sel_hi:[0,1,1]
	v_mul_f32_e32 v122, 0x3fcc422a, v122
	v_mul_f32_e32 v121, 0xbfb8aa3b, v121
	v_exp_f32_e32 v120, v120
	v_add_f32_e32 v116, 1.0, v116
	v_rcp_f32_e32 v115, v115
	v_fma_mix_f32 v142, v111, v36, v142 op_sel:[0,1,0] op_sel_hi:[0,1,0]
	v_cvt_f32_f16_e32 v138, v58
	v_mul_f32_e32 v125, v190, v125
	v_fma_mix_f32 v124, v124, v35, v35 op_sel_hi:[0,1,1]
	v_mul_f32_e32 v123, 0x3fcc422a, v123
	v_mul_f32_e32 v122, 0xbfb8aa3b, v122
	v_exp_f32_e32 v121, v121
	v_add_f32_e32 v117, 1.0, v117
	v_rcp_f32_e32 v116, v116
	v_fma_mix_f32 v142, v112, v37, v142 op_sel_hi:[0,1,0]
	v_cvt_f32_f16_sdwa v139, v58 dst_sel:DWORD dst_unused:UNUSED_PAD src0_sel:WORD_1
	v_mul_f32_e32 v143, 0x3d372713, v135
	v_fma_mix_f32 v125, v125, v35, v35 op_sel:[0,1,1] op_sel_hi:[0,1,1]
	v_mul_f32_e32 v124, 0x3fcc422a, v124
	v_mul_f32_e32 v123, 0xbfb8aa3b, v123
	v_exp_f32_e32 v122, v122
	v_add_f32_e32 v118, 1.0, v118
	v_rcp_f32_e32 v117, v117
	v_fma_mix_f32 v142, v113, v37, v142 op_sel:[0,1,0] op_sel_hi:[0,1,0]
	v_cvt_f32_f16_e32 v140, v59
	v_mul_f32_e32 v144, 0x3d372713, v136
	v_mul_f32_e32 v135, v143, v135
	v_mul_f32_e32 v125, 0x3fcc422a, v125
	v_fma_mix_f32 v134, v134, v56, v56 op_sel_hi:[0,1,1]
	v_mul_f32_e32 v124, 0xbfb8aa3b, v124
	v_exp_f32_e32 v123, v123
	v_add_f32_e32 v119, 1.0, v119
	v_rcp_f32_e32 v118, v118
	v_fma_mix_f32 v142, v114, v38, v142 op_sel_hi:[0,1,0]
	v_cvt_f32_f16_sdwa v141, v59 dst_sel:DWORD dst_unused:UNUSED_PAD src0_sel:WORD_1
	v_mul_f32_e32 v145, 0x3d372713, v137
	v_mul_f32_e32 v136, v144, v136
	v_fma_mix_f32 v135, v135, v56, v56 op_sel:[0,1,1] op_sel_hi:[0,1,1]
	v_mul_f32_e32 v125, 0xbfb8aa3b, v125
	v_mul_f32_e32 v134, 0x3fcc422a, v134
	v_exp_f32_e32 v124, v124
	v_add_f32_e32 v120, 1.0, v120
	v_rcp_f32_e32 v119, v119
	v_fma_mix_f32 v142, v115, v38, v142 op_sel:[0,1,0] op_sel_hi:[0,1,0]
	v_mul_f32_e32 v146, 0x3d372713, v138
	v_mul_f32_e32 v137, v145, v137
	v_fma_mix_f32 v136, v136, v57, v57 op_sel_hi:[0,1,1]
	v_mul_f32_e32 v135, 0x3fcc422a, v135
	v_exp_f32_e32 v125, v125
	v_mul_f32_e32 v134, 0xbfb8aa3b, v134
	v_add_f32_e32 v121, 1.0, v121
	v_rcp_f32_e32 v120, v120
	v_fma_mix_f32 v142, v116, v39, v142 op_sel_hi:[0,1,0]
	v_mul_f32_e32 v147, 0x3d372713, v139
	v_mul_f32_e32 v138, v146, v138
	v_fma_mix_f32 v137, v137, v57, v57 op_sel:[0,1,1] op_sel_hi:[0,1,1]
	v_mul_f32_e32 v136, 0x3fcc422a, v136
	v_mul_f32_e32 v135, 0xbfb8aa3b, v135
	v_exp_f32_e32 v134, v134
	v_add_f32_e32 v122, 1.0, v122
	v_rcp_f32_e32 v121, v121
	v_fma_mix_f32 v142, v117, v39, v142 op_sel:[0,1,0] op_sel_hi:[0,1,0]
	v_mul_f32_e32 v148, 0x3d372713, v140
	v_mul_f32_e32 v139, v147, v139
	v_fma_mix_f32 v138, v138, v58, v58 op_sel_hi:[0,1,1]
	v_mul_f32_e32 v137, 0x3fcc422a, v137
	v_mul_f32_e32 v136, 0xbfb8aa3b, v136
	v_exp_f32_e32 v135, v135
	v_add_f32_e32 v123, 1.0, v123
	v_rcp_f32_e32 v122, v122
	v_fma_mix_f32 v142, v118, v32, v142 op_sel_hi:[0,1,0]
	v_mul_f32_e32 v149, 0x3d372713, v141
	v_mul_f32_e32 v140, v148, v140
	v_fma_mix_f32 v139, v139, v58, v58 op_sel:[0,1,1] op_sel_hi:[0,1,1]
	v_mul_f32_e32 v138, 0x3fcc422a, v138
	v_mul_f32_e32 v137, 0xbfb8aa3b, v137
	v_exp_f32_e32 v136, v136
	v_add_f32_e32 v124, 1.0, v124
	v_rcp_f32_e32 v123, v123
	v_fma_mix_f32 v142, v119, v32, v142 op_sel:[0,1,0] op_sel_hi:[0,1,0]
	v_mul_f32_e32 v141, v149, v141
	v_fma_mix_f32 v140, v140, v59, v59 op_sel_hi:[0,1,1]
	v_mul_f32_e32 v139, 0x3fcc422a, v139
	v_mul_f32_e32 v138, 0xbfb8aa3b, v138
	v_exp_f32_e32 v137, v137
	v_add_f32_e32 v125, 1.0, v125
	v_rcp_f32_e32 v124, v124
	v_fma_mix_f32 v142, v120, v33, v142 op_sel_hi:[0,1,0]
	v_fma_mix_f32 v141, v141, v59, v59 op_sel:[0,1,1] op_sel_hi:[0,1,1]
	v_mul_f32_e32 v140, 0x3fcc422a, v140
	v_mul_f32_e32 v139, 0xbfb8aa3b, v139
	v_exp_f32_e32 v138, v138
	v_rcp_f32_e32 v125, v125
	v_add_f32_e32 v134, 1.0, v134
	v_fma_mix_f32 v142, v121, v33, v142 op_sel:[0,1,0] op_sel_hi:[0,1,0]
	v_mul_f32_e32 v141, 0x3fcc422a, v141
	v_mul_f32_e32 v140, 0xbfb8aa3b, v140
	v_exp_f32_e32 v139, v139
	v_add_f32_e32 v135, 1.0, v135
	v_rcp_f32_e32 v134, v134
	v_fma_mix_f32 v142, v122, v34, v142 op_sel_hi:[0,1,0]
	v_mul_f32_e32 v141, 0xbfb8aa3b, v141
	v_exp_f32_e32 v140, v140
	v_add_f32_e32 v136, 1.0, v136
	v_rcp_f32_e32 v135, v135
	v_fma_mix_f32 v142, v123, v34, v142 op_sel:[0,1,0] op_sel_hi:[0,1,0]
	v_exp_f32_e32 v141, v141
	v_add_f32_e32 v137, 1.0, v137
	v_rcp_f32_e32 v136, v136
	v_fma_mix_f32 v142, v124, v35, v142 op_sel_hi:[0,1,0]
	v_add_f32_e32 v138, 1.0, v138
	v_rcp_f32_e32 v137, v137
	v_fma_mix_f32 v142, v125, v35, v142 op_sel:[0,1,0] op_sel_hi:[0,1,0]
	v_add_f32_e32 v139, 1.0, v139
	v_rcp_f32_e32 v138, v138
	v_fma_mix_f32 v142, v134, v56, v142 op_sel_hi:[0,1,0]
	v_add_f32_e32 v140, 1.0, v140
	v_rcp_f32_e32 v139, v139
	v_fma_mix_f32 v142, v135, v56, v142 op_sel:[0,1,0] op_sel_hi:[0,1,0]
	v_add_f32_e32 v141, 1.0, v141
	v_rcp_f32_e32 v140, v140
	v_fma_mix_f32 v142, v136, v57, v142 op_sel_hi:[0,1,0]
	v_rcp_f32_e32 v141, v141
	v_fma_mix_f32 v142, v137, v57, v142 op_sel:[0,1,0] op_sel_hi:[0,1,0]
	v_fma_mix_f32 v142, v138, v58, v142 op_sel_hi:[0,1,0]
	v_fma_mix_f32 v142, v139, v58, v142 op_sel:[0,1,0] op_sel_hi:[0,1,0]
	v_fma_mix_f32 v142, v140, v59, v142 op_sel_hi:[0,1,0]
	v_fma_mix_f32 v142, v141, v59, v142 op_sel:[0,1,0] op_sel_hi:[0,1,0]
	v_mul_f32_e32 v142, 0x3c800000, v142
	v_fma_mix_f32 v126, v126, v60, -v142 op_sel_hi:[0,1,0]
; __global__ void __launch_bounds__(512, 2) fwd_megakernel(Params p) {
;     ...
;                     const float mean = s * (1.0f / 64.0f); float s2 = 0.f;
; #pragma unroll
;                     for (int d = 0; d < 64; ++d) { v[d] -= mean; s2 += v[d] * v[d]; }
	v_fma_mix_f32 v60, v127, v60, -v142 op_sel:[0,1,0] op_sel_hi:[0,1,0]
	v_fma_mix_f32 v78, v78, v52, -v142 op_sel_hi:[0,1,0]
	v_fma_mix_f32 v52, v79, v52, -v142 op_sel:[0,1,0] op_sel_hi:[0,1,0]
	v_fma_mix_f32 v79, v80, v53, -v142 op_sel_hi:[0,1,0]
	v_fma_mix_f32 v80, v82, v54, -v142 op_sel_hi:[0,1,0]
	v_fma_mix_f32 v54, v83, v54, -v142 op_sel:[0,1,0] op_sel_hi:[0,1,0]
	v_fma_mix_f32 v82, v86, v48, -v142 op_sel_hi:[0,1,0]
	v_fma_mix_f32 v48, v87, v48, -v142 op_sel:[0,1,0] op_sel_hi:[0,1,0]
	v_fma_mix_f32 v83, v88, v49, -v142 op_sel_hi:[0,1,0]
	v_fma_mix_f32 v49, v89, v49, -v142 op_sel:[0,1,0] op_sel_hi:[0,1,0]
	v_fma_mix_f32 v86, v94, v44, -v142 op_sel_hi:[0,1,0]
	v_fma_mix_f32 v87, v95, v44, -v142 op_sel:[0,1,0] op_sel_hi:[0,1,0]
	v_fma_mix_f32 v88, v96, v45, -v142 op_sel_hi:[0,1,0]
	v_fma_mix_f32 v89, v97, v45, -v142 op_sel:[0,1,0] op_sel_hi:[0,1,0]
	v_fma_mix_f32 v94, v102, v40, -v142 op_sel_hi:[0,1,0]
	v_fma_mix_f32 v95, v103, v40, -v142 op_sel:[0,1,0] op_sel_hi:[0,1,0]
	v_fma_mix_f32 v96, v104, v41, -v142 op_sel_hi:[0,1,0]
	v_fma_mix_f32 v97, v105, v41, -v142 op_sel:[0,1,0] op_sel_hi:[0,1,0]
	v_fma_mix_f32 v40, v134, v56, -v142 op_sel_hi:[0,1,0]
	v_fma_mix_f32 v41, v135, v56, -v142 op_sel:[0,1,0] op_sel_hi:[0,1,0]
	v_mul_f32_e32 v56, v60, v60
	v_fma_mix_f32 v127, v128, v61, -v142 op_sel_hi:[0,1,0]
	v_fmac_f32_e32 v56, v126, v126
	v_fma_mix_f32 v61, v129, v61, -v142 op_sel:[0,1,0] op_sel_hi:[0,1,0]
	v_fmac_f32_e32 v56, v127, v127
	v_fma_mix_f32 v128, v130, v62, -v142 op_sel_hi:[0,1,0]
	v_fmac_f32_e32 v56, v61, v61
	v_fma_mix_f32 v62, v131, v62, -v142 op_sel:[0,1,0] op_sel_hi:[0,1,0]
	v_fmac_f32_e32 v56, v128, v128
	v_fma_mix_f32 v129, v132, v63, -v142 op_sel_hi:[0,1,0]
	v_fmac_f32_e32 v56, v62, v62
	v_fma_mix_f32 v63, v133, v63, -v142 op_sel:[0,1,0] op_sel_hi:[0,1,0]
	v_fmac_f32_e32 v56, v129, v129
	v_fmac_f32_e32 v56, v63, v63
	v_fmac_f32_e32 v56, v78, v78
	v_fmac_f32_e32 v56, v52, v52
	v_fma_mix_f32 v53, v81, v53, -v142 op_sel:[0,1,0] op_sel_hi:[0,1,0]
	v_fmac_f32_e32 v56, v79, v79
	v_fmac_f32_e32 v56, v53, v53
	v_fmac_f32_e32 v56, v80, v80
	v_fma_mix_f32 v81, v84, v55, -v142 op_sel_hi:[0,1,0]
	v_fmac_f32_e32 v56, v54, v54
	v_fma_mix_f32 v55, v85, v55, -v142 op_sel:[0,1,0] op_sel_hi:[0,1,0]
	v_fmac_f32_e32 v56, v81, v81
	v_fmac_f32_e32 v56, v55, v55
	v_fmac_f32_e32 v56, v82, v82
	v_fmac_f32_e32 v56, v48, v48
	v_fmac_f32_e32 v56, v83, v83
	v_fma_mix_f32 v84, v90, v50, -v142 op_sel_hi:[0,1,0]
	v_fmac_f32_e32 v56, v49, v49
	v_fma_mix_f32 v50, v91, v50, -v142 op_sel:[0,1,0] op_sel_hi:[0,1,0]
	v_fmac_f32_e32 v56, v84, v84
	v_fma_mix_f32 v85, v92, v51, -v142 op_sel_hi:[0,1,0]
	v_fmac_f32_e32 v56, v50, v50
	v_fma_mix_f32 v51, v93, v51, -v142 op_sel:[0,1,0] op_sel_hi:[0,1,0]
	v_fmac_f32_e32 v56, v85, v85
	v_fmac_f32_e32 v56, v51, v51
	v_fmac_f32_e32 v56, v86, v86
	v_fmac_f32_e32 v56, v87, v87
	v_fmac_f32_e32 v56, v88, v88
	v_fma_mix_f32 v90, v98, v46, -v142 op_sel_hi:[0,1,0]
	v_fmac_f32_e32 v56, v89, v89
	v_fma_mix_f32 v91, v99, v46, -v142 op_sel:[0,1,0] op_sel_hi:[0,1,0]
	v_fmac_f32_e32 v56, v90, v90
	v_fma_mix_f32 v92, v100, v47, -v142 op_sel_hi:[0,1,0]
	v_fmac_f32_e32 v56, v91, v91
	v_fma_mix_f32 v93, v101, v47, -v142 op_sel:[0,1,0] op_sel_hi:[0,1,0]
	v_fmac_f32_e32 v56, v92, v92
	v_fmac_f32_e32 v56, v93, v93
	v_fmac_f32_e32 v56, v94, v94
	v_fmac_f32_e32 v56, v95, v95
	v_fmac_f32_e32 v56, v96, v96
	v_fma_mix_f32 v98, v106, v42, -v142 op_sel_hi:[0,1,0]
	v_fmac_f32_e32 v56, v97, v97
	v_fma_mix_f32 v99, v107, v42, -v142 op_sel:[0,1,0] op_sel_hi:[0,1,0]
	v_fmac_f32_e32 v56, v98, v98
	v_fma_mix_f32 v100, v108, v43, -v142 op_sel_hi:[0,1,0]
	v_fmac_f32_e32 v56, v99, v99
	v_fma_mix_f32 v101, v109, v43, -v142 op_sel:[0,1,0] op_sel_hi:[0,1,0]
	v_fmac_f32_e32 v56, v100, v100
	v_fma_mix_f32 v102, v110, v36, -v142 op_sel_hi:[0,1,0]
	v_fmac_f32_e32 v56, v101, v101
	v_fma_mix_f32 v103, v111, v36, -v142 op_sel:[0,1,0] op_sel_hi:[0,1,0]
	v_fmac_f32_e32 v56, v102, v102
	v_fma_mix_f32 v104, v112, v37, -v142 op_sel_hi:[0,1,0]
	v_fmac_f32_e32 v56, v103, v103
	v_fma_mix_f32 v105, v113, v37, -v142 op_sel:[0,1,0] op_sel_hi:[0,1,0]
	v_fmac_f32_e32 v56, v104, v104
	v_fma_mix_f32 v106, v114, v38, -v142 op_sel_hi:[0,1,0]
	v_fmac_f32_e32 v56, v105, v105
	v_fma_mix_f32 v107, v115, v38, -v142 op_sel:[0,1,0] op_sel_hi:[0,1,0]
	v_fmac_f32_e32 v56, v106, v106
	v_fma_mix_f32 v108, v116, v39, -v142 op_sel_hi:[0,1,0]
	v_fmac_f32_e32 v56, v107, v107
	v_fma_mix_f32 v109, v117, v39, -v142 op_sel:[0,1,0] op_sel_hi:[0,1,0]
	v_fmac_f32_e32 v56, v108, v108
	v_fma_mix_f32 v36, v118, v32, -v142 op_sel_hi:[0,1,0]
	v_fmac_f32_e32 v56, v109, v109
	v_fma_mix_f32 v32, v119, v32, -v142 op_sel:[0,1,0] op_sel_hi:[0,1,0]
	v_fmac_f32_e32 v56, v36, v36
	v_fma_mix_f32 v37, v120, v33, -v142 op_sel_hi:[0,1,0]
	v_fmac_f32_e32 v56, v32, v32
	v_fma_mix_f32 v33, v121, v33, -v142 op_sel:[0,1,0] op_sel_hi:[0,1,0]
	v_fmac_f32_e32 v56, v37, v37
	v_fma_mix_f32 v38, v122, v34, -v142 op_sel_hi:[0,1,0]
	v_fmac_f32_e32 v56, v33, v33
	v_fma_mix_f32 v34, v123, v34, -v142 op_sel:[0,1,0] op_sel_hi:[0,1,0]
	v_fmac_f32_e32 v56, v38, v38
	v_fma_mix_f32 v39, v124, v35, -v142 op_sel_hi:[0,1,0]
	v_fmac_f32_e32 v56, v34, v34
	v_fma_mix_f32 v35, v125, v35, -v142 op_sel:[0,1,0] op_sel_hi:[0,1,0]
	v_fmac_f32_e32 v56, v39, v39
	v_fmac_f32_e32 v56, v35, v35
	v_fmac_f32_e32 v56, v40, v40
	v_fma_mix_f32 v42, v136, v57, -v142 op_sel_hi:[0,1,0]
	v_fmac_f32_e32 v56, v41, v41
	v_fma_mix_f32 v43, v137, v57, -v142 op_sel:[0,1,0] op_sel_hi:[0,1,0]
	v_fmac_f32_e32 v56, v42, v42
	v_fma_mix_f32 v44, v138, v58, -v142 op_sel_hi:[0,1,0]
	v_fmac_f32_e32 v56, v43, v43
	v_fma_mix_f32 v45, v139, v58, -v142 op_sel:[0,1,0] op_sel_hi:[0,1,0]
; __device__ __forceinline__ unsigned cvt_pk_bf16(float lo, float hi) { const f32x2 v = (f32x2){lo, hi}; const bf16v2 b = __builtin_convertvector(v, bf16v2); return __builtin_bit_cast(unsigned, b); }
; __global__ void __launch_bounds__(512, 2) fwd_megakernel(Params p) {
;     ...
;                     for (int d = 0; d < 64; ++d) { v[d] -= mean; s2 += v[d] * v[d]; }
;                     const float rstd = 1.0f / sqrtf(s2 * (1.0f / 64.0f) + LN_EPS);
;                     bf16_t* dst = VT + ((size_t)bn * 16 + g) * 64 * 128 + q;
; #pragma unroll
;                     for (int d = 0; d < 64; ++d) { const float o = v[d] * rstd * gg[g * 64 + d] + gb[g * 64 + d]; dst[d * 128] = (bf16_t)(cvt_pk_bf16(o, 0.f) & 0xffffu); }
	v_fmac_f32_e32 v56, v44, v44
	v_fma_mix_f32 v46, v140, v59, -v142 op_sel_hi:[0,1,0]
	v_fmac_f32_e32 v56, v45, v45
	v_fma_mix_f32 v47, v141, v59, -v142 op_sel:[0,1,0] op_sel_hi:[0,1,0]
	v_fmac_f32_e32 v56, v46, v46
	v_fmac_f32_e32 v56, v47, v47
	v_fmamk_f32 v56, v56, 0x3c800000, v75
	v_mul_f32_e32 v57, 0x4f800000, v56
	v_cmp_gt_f32_e32 vcc, s22, v56
	s_nop 1
	v_cndmask_b32_e32 v56, v56, v57, vcc
	v_sqrt_f32_e32 v57, v56
	s_nop 0
	v_add_u32_e32 v58, -1, v57
	v_add_u32_e32 v59, 1, v57
	v_fma_f32 v110, -v58, v57, v56
	v_fma_f32 v111, -v59, v57, v56
	v_cmp_ge_f32_e64 s[0:1], 0, v110
	s_nop 1
	v_cndmask_b32_e64 v57, v57, v58, s[0:1]
	v_cmp_lt_f32_e64 s[0:1], 0, v111
	s_nop 1
	v_cndmask_b32_e64 v57, v57, v59, s[0:1]
	v_mul_f32_e32 v58, 0x37800000, v57
	v_cndmask_b32_e32 v57, v57, v58, vcc
	v_cmp_class_f32_e32 vcc, v56, v76
	s_nop 1
	v_cndmask_b32_e32 v56, v57, v56, vcc
	v_div_scale_f32 v57, s[0:1], v56, v56, 1.0
	v_rcp_f32_e32 v59, v57
	v_div_scale_f32 v58, vcc, 1.0, v56, 1.0
	v_fma_f32 v110, -v57, v59, 1.0
	v_fmac_f32_e32 v59, v110, v59
	v_mul_f32_e32 v110, v58, v59
	v_fma_f32 v111, -v57, v110, v58
	v_fmac_f32_e32 v110, v111, v59
	v_fma_f32 v57, -v57, v110, v58
	v_div_fmas_f32 v57, v57, v59, v110
	v_div_fixup_f32 v56, v57, v56, 1.0
	v_mul_f32_e32 v57, v56, v126
	v_mul_f32_e32 v58, v56, v60
	v_mul_f32_e32 v59, v56, v127
	v_mul_f32_e32 v60, v56, v61
	v_mul_f32_e32 v61, v56, v128
	v_mul_f32_e32 v62, v56, v62
	v_mul_f32_e32 v110, v56, v129
	v_mul_f32_e32 v63, v56, v63
	v_mul_f32_e32 v78, v56, v78
	v_mul_f32_e32 v52, v56, v52
	v_mul_f32_e32 v79, v56, v79
	v_mul_f32_e32 v53, v56, v53
	v_mul_f32_e32 v80, v56, v80
	v_mul_f32_e32 v54, v56, v54
	v_mul_f32_e32 v81, v56, v81
	v_mul_f32_e32 v55, v56, v55
	v_fma_f32 v16, v57, v28, v16
	v_fma_f32 v17, v58, v29, v17
	v_fma_f32 v18, v59, v30, v18
	v_fmac_f32_e32 v19, v60, v31
	v_fma_f32 v12, v61, v24, v12
	v_fma_f32 v13, v62, v25, v13
	v_fma_f32 v14, v110, v26, v14
	v_fmac_f32_e32 v15, v63, v27
	v_fma_f32 v4, v78, v20, v4
	v_fma_f32 v5, v52, v21, v5
	v_fma_f32 v6, v79, v22, v6
	v_fmac_f32_e32 v7, v53, v23
	v_fma_f32 v0, v80, v8, v0
	v_fma_f32 v1, v54, v9, v1
	v_fma_f32 v2, v81, v10, v2
	v_fmac_f32_e32 v3, v55, v11
	v_cvt_pk_bf16_f32 v8, v16, s0
	v_cvt_pk_bf16_f32 v9, v17, s0
	v_cvt_pk_bf16_f32 v10, v18, s0
	v_cvt_pk_bf16_f32 v11, v19, s0
	v_cvt_pk_bf16_f32 v12, v12, s0
	v_cvt_pk_bf16_f32 v13, v13, s0
	v_cvt_pk_bf16_f32 v14, v14, s0
	v_cvt_pk_bf16_f32 v15, v15, s0
	v_cvt_pk_bf16_f32 v4, v4, s0
	v_cvt_pk_bf16_f32 v5, v5, s0
	v_cvt_pk_bf16_f32 v6, v6, s0
	v_cvt_pk_bf16_f32 v7, v7, s0
	v_cvt_pk_bf16_f32 v0, v0, s0
	v_cvt_pk_bf16_f32 v1, v1, s0
	v_cvt_pk_bf16_f32 v2, v2, s0
	v_cvt_pk_bf16_f32 v3, v3, s0
	global_store_short v66, v8, s[6:7]
	global_store_short v66, v9, s[6:7] offset:256
	global_store_short v66, v10, s[6:7] offset:512
	global_store_short v66, v11, s[6:7] offset:768
	global_store_short v66, v12, s[6:7] offset:1024
	global_store_short v66, v13, s[6:7] offset:1280
	global_store_short v66, v14, s[6:7] offset:1536
	global_store_short v66, v15, s[6:7] offset:1792
	global_store_short v66, v4, s[6:7] offset:2048
	global_store_short v66, v5, s[6:7] offset:2304
	global_store_short v66, v6, s[6:7] offset:2560
	global_store_short v66, v7, s[6:7] offset:2816
	global_store_short v66, v0, s[6:7] offset:3072
	global_store_short v66, v1, s[6:7] offset:3328
	global_store_short v66, v2, s[6:7] offset:3584
	global_store_short v66, v3, s[6:7] offset:3840
	global_load_dwordx4 v[0:3], v77, s[12:13] offset:128
	s_nop 0
	global_load_dwordx4 v[4:7], v77, s[14:15] offset:128
	global_load_dwordx4 v[8:11], v77, s[12:13] offset:144
	global_load_dwordx4 v[12:15], v77, s[14:15] offset:144
	global_load_dwordx4 v[16:19], v77, s[12:13] offset:160
	global_load_dwordx4 v[20:23], v77, s[14:15] offset:160
	global_load_dwordx4 v[24:27], v77, s[12:13] offset:176
	global_load_dwordx4 v[28:31], v77, s[14:15] offset:176
	v_mul_f32_e32 v82, v56, v82
	v_mul_f32_e32 v48, v56, v48
	v_mul_f32_e32 v83, v56, v83
	v_mul_f32_e32 v49, v56, v49
	v_mul_f32_e32 v84, v56, v84
	v_mul_f32_e32 v50, v56, v50
	v_mul_f32_e32 v85, v56, v85
	v_mul_f32_e32 v51, v56, v51
	v_mul_f32_e32 v86, v56, v86
	v_mul_f32_e32 v87, v56, v87
	v_mul_f32_e32 v88, v56, v88
	v_mul_f32_e32 v89, v56, v89
	v_mul_f32_e32 v90, v56, v90
	v_mul_f32_e32 v91, v56, v91
	v_mul_f32_e32 v92, v56, v92
	v_mul_f32_e32 v93, v56, v93
	v_mul_f32_e32 v94, v56, v94
	v_mul_f32_e32 v95, v56, v95
	v_mul_f32_e32 v96, v56, v96
	v_mul_f32_e32 v97, v56, v97
	v_mul_f32_e32 v98, v56, v98
	v_mul_f32_e32 v99, v56, v99
	v_mul_f32_e32 v100, v56, v100
	v_mul_f32_e32 v101, v56, v101
	v_mul_f32_e32 v102, v56, v102
	v_mul_f32_e32 v103, v56, v103
	v_mul_f32_e32 v104, v56, v104
	v_mul_f32_e32 v105, v56, v105
	v_mul_f32_e32 v106, v56, v106
	v_mul_f32_e32 v107, v56, v107
	v_mul_f32_e32 v108, v56, v108
	v_mul_f32_e32 v109, v56, v109
	v_mul_f32_e32 v36, v56, v36
	v_mul_f32_e32 v32, v56, v32
	v_mul_f32_e32 v37, v56, v37
	v_mul_f32_e32 v33, v56, v33
	v_mul_f32_e32 v38, v56, v38
	v_mul_f32_e32 v34, v56, v34
	v_mul_f32_e32 v39, v56, v39
	v_mul_f32_e32 v35, v56, v35
	v_mul_f32_e32 v40, v56, v40
	v_mul_f32_e32 v41, v56, v41
	v_mul_f32_e32 v42, v56, v42
	v_mul_f32_e32 v43, v56, v43
	v_mul_f32_e32 v44, v56, v44
	v_mul_f32_e32 v45, v56, v45
	v_mul_f32_e32 v46, v56, v46
	v_mul_f32_e32 v47, v56, v47
	s_nop 0
	v_fma_f32 v200, v82, v200, v204
	v_fma_f32 v201, v48, v201, v205
	v_fma_f32 v202, v83, v202, v206
	v_fmac_f32_e32 v207, v49, v203
	v_fma_f32 v203, v84, v208, v212
	v_fma_f32 v204, v50, v209, v213
	v_fma_f32 v205, v85, v210, v214
	v_fmac_f32_e32 v215, v51, v211
	v_fma_f32 v206, v86, v216, v220
	v_fma_f32 v208, v87, v217, v221
; __device__ __forceinline__ unsigned cvt_pk_bf16(float lo, float hi) { const f32x2 v = (f32x2){lo, hi}; const bf16v2 b = __builtin_convertvector(v, bf16v2); return __builtin_bit_cast(unsigned, b); }
; __global__ void __launch_bounds__(512, 2) fwd_megakernel(Params p) {
;     ...
; #pragma unroll
;                     for (int d = 0; d < 64; ++d) { const float o = v[d] * rstd * gg[g * 64 + d] + gb[g * 64 + d]; dst[d * 128] = (bf16_t)(cvt_pk_bf16(o, 0.f) & 0xffffu); }
	v_fma_f32 v209, v88, v218, v222
	v_fmac_f32_e32 v223, v89, v219
	v_fma_f32 v210, v90, v224, v228
	v_fma_f32 v211, v91, v225, v229
	v_fma_f32 v212, v92, v226, v230
	v_fmac_f32_e32 v231, v93, v227
	v_cvt_pk_bf16_f32 v200, v200, s0
	v_cvt_pk_bf16_f32 v201, v201, s0
	v_cvt_pk_bf16_f32 v202, v202, s0
	v_cvt_pk_bf16_f32 v207, v207, s0
	v_cvt_pk_bf16_f32 v203, v203, s0
	v_cvt_pk_bf16_f32 v204, v204, s0
	v_cvt_pk_bf16_f32 v205, v205, s0
	v_cvt_pk_bf16_f32 v213, v215, s0
	v_cvt_pk_bf16_f32 v206, v206, s0
	v_cvt_pk_bf16_f32 v208, v208, s0
	v_cvt_pk_bf16_f32 v209, v209, s0
	v_cvt_pk_bf16_f32 v214, v223, s0
	v_cvt_pk_bf16_f32 v210, v210, s0
	v_cvt_pk_bf16_f32 v211, v211, s0
	v_cvt_pk_bf16_f32 v212, v212, s0
	v_cvt_pk_bf16_f32 v215, v231, s0
	global_store_short v[70:71], v200, off offset:-4096
	global_store_short v[72:73], v201, off offset:256
	global_store_short v[72:73], v202, off offset:512
	global_store_short v[72:73], v207, off offset:768
	global_store_short v[72:73], v203, off offset:1024
	global_store_short v[72:73], v204, off offset:1280
	global_store_short v[72:73], v205, off offset:1536
	global_store_short v[72:73], v213, off offset:1792
	global_store_short v[72:73], v206, off offset:2048
	global_store_short v[72:73], v208, off offset:2304
	global_store_short v[72:73], v209, off offset:2560
	global_store_short v[72:73], v214, off offset:2816
	global_store_short v[72:73], v210, off offset:3072
	global_store_short v[72:73], v211, off offset:3328
	global_store_short v[72:73], v212, off offset:3584
	global_store_short v[72:73], v215, off offset:3840
	global_load_dwordx4 v[200:203], v77, s[12:13] offset:192
	global_load_dwordx4 v[204:207], v77, s[14:15] offset:192
	s_nop 0
	global_load_dwordx4 v[208:211], v77, s[12:13] offset:208
	global_load_dwordx4 v[212:215], v77, s[14:15] offset:208
	global_load_dwordx4 v[216:219], v77, s[12:13] offset:224
	global_load_dwordx4 v[220:223], v77, s[14:15] offset:224
	global_load_dwordx4 v[224:227], v77, s[12:13] offset:240
	global_load_dwordx4 v[228:231], v77, s[14:15] offset:240
	v_add_co_u32_e32 v48, vcc, s31, v68
	s_waitcnt vmcnt(24)
	v_fma_f32 v0, v94, v0, v4
	v_fma_f32 v1, v95, v1, v5
	v_fma_f32 v2, v96, v2, v6
	v_fmac_f32_e32 v7, v97, v3
	v_fma_f32 v3, v98, v8, v12
	v_fma_f32 v4, v99, v9, v13
	v_fma_f32 v5, v100, v10, v14
	v_fmac_f32_e32 v15, v101, v11
	v_fma_f32 v6, v102, v16, v20
	v_fma_f32 v8, v103, v17, v21
	v_fma_f32 v9, v104, v18, v22
	v_fmac_f32_e32 v23, v105, v19
	v_fma_f32 v10, v106, v24, v28
	v_fma_f32 v11, v107, v25, v29
	v_fma_f32 v12, v108, v26, v30
	v_fmac_f32_e32 v31, v109, v27
	v_cvt_pk_bf16_f32 v0, v0, s0
	v_cvt_pk_bf16_f32 v1, v1, s0
	v_cvt_pk_bf16_f32 v2, v2, s0
	v_cvt_pk_bf16_f32 v7, v7, s0
	v_cvt_pk_bf16_f32 v3, v3, s0
	v_cvt_pk_bf16_f32 v4, v4, s0
	v_cvt_pk_bf16_f32 v5, v5, s0
	v_cvt_pk_bf16_f32 v13, v15, s0
	v_cvt_pk_bf16_f32 v6, v6, s0
	v_cvt_pk_bf16_f32 v8, v8, s0
	v_cvt_pk_bf16_f32 v9, v9, s0
	v_cvt_pk_bf16_f32 v14, v23, s0
	v_cvt_pk_bf16_f32 v10, v10, s0
	v_cvt_pk_bf16_f32 v11, v11, s0
	v_cvt_pk_bf16_f32 v12, v12, s0
	v_cvt_pk_bf16_f32 v15, v31, s0
	global_store_short v[70:71], v0, off
	global_store_short v[70:71], v1, off offset:256
	global_store_short v[70:71], v2, off offset:512
	global_store_short v[70:71], v7, off offset:768
	global_store_short v[70:71], v3, off offset:1024
	global_store_short v[70:71], v4, off offset:1280
	global_store_short v[70:71], v5, off offset:1536
	global_store_short v[70:71], v13, off offset:1792
	global_store_short v[70:71], v6, off offset:2048
	global_store_short v[70:71], v8, off offset:2304
	global_store_short v[70:71], v9, off offset:2560
	global_store_short v[70:71], v14, off offset:2816
	global_store_short v[70:71], v10, off offset:3072
	global_store_short v[70:71], v11, off offset:3328
	global_store_short v[70:71], v12, off offset:3584
	global_store_short v[70:71], v15, off offset:3840
	s_nop 0
	s_nop 0
	s_nop 0
	s_nop 0
	s_nop 0
	s_nop 0
	s_nop 0
	s_nop 0
	s_nop 0
	v_addc_co_u32_e32 v49, vcc, 0, v69, vcc
	s_waitcnt vmcnt(16)
	v_fma_f32 v200, v36, v200, v204
	v_fma_f32 v201, v32, v201, v205
	v_fma_f32 v202, v37, v202, v206
	v_fmac_f32_e32 v207, v33, v203
	v_fma_f32 v203, v38, v208, v212
	v_fma_f32 v204, v34, v209, v213
	v_fma_f32 v205, v39, v210, v214
	v_fmac_f32_e32 v215, v35, v211
	v_fma_f32 v206, v40, v216, v220
	v_fma_f32 v208, v41, v217, v221
	v_fma_f32 v209, v42, v218, v222
	v_fmac_f32_e32 v223, v43, v219
	v_fma_f32 v210, v44, v224, v228
	v_fma_f32 v211, v45, v225, v229
	v_fma_f32 v212, v46, v226, v230
	v_fmac_f32_e32 v231, v47, v227
	v_cvt_pk_bf16_f32 v200, v200, s0
	v_cvt_pk_bf16_f32 v201, v201, s0
	v_cvt_pk_bf16_f32 v202, v202, s0
	v_cvt_pk_bf16_f32 v207, v207, s0
	v_cvt_pk_bf16_f32 v203, v203, s0
	v_cvt_pk_bf16_f32 v204, v204, s0
	v_cvt_pk_bf16_f32 v205, v205, s0
	v_cvt_pk_bf16_f32 v213, v215, s0
	v_cvt_pk_bf16_f32 v206, v206, s0
	v_cvt_pk_bf16_f32 v208, v208, s0
	v_cvt_pk_bf16_f32 v209, v209, s0
	v_cvt_pk_bf16_f32 v214, v223, s0
	v_cvt_pk_bf16_f32 v210, v210, s0
	v_cvt_pk_bf16_f32 v211, v211, s0
	v_cvt_pk_bf16_f32 v212, v212, s0
	v_cvt_pk_bf16_f32 v215, v231, s0
	global_store_short v[48:49], v200, off
	global_store_short v[48:49], v201, off offset:256
	global_store_short v[48:49], v202, off offset:512
	global_store_short v[48:49], v207, off offset:768
	global_store_short v[48:49], v203, off offset:1024
	global_store_short v[48:49], v204, off offset:1280
	global_store_short v[48:49], v205, off offset:1536
	global_store_short v[48:49], v213, off offset:1792
	global_store_short v[48:49], v206, off offset:2048
	global_store_short v[48:49], v208, off offset:2304
	global_store_short v[48:49], v209, off offset:2560
	global_store_short v[48:49], v214, off offset:2816
	global_store_short v[48:49], v210, off offset:3072
	global_store_short v[48:49], v211, off offset:3328
	global_store_short v[48:49], v212, off offset:3584
	global_store_short v[48:49], v215, off offset:3840
	s_cbranch_scc1 .LBB0_574

; #define LAS __attribute__((address_space(3)))
; __device__ __forceinline__ unsigned cvt_pk_bf16(float lo, float hi) { const f32x2 v = (f32x2){lo, hi}; const bf16v2 b = __builtin_convertvector(v, bf16v2); return __builtin_bit_cast(unsigned, b); }
; __global__ void __launch_bounds__(512, 2) fwd_megakernel(Params p) {
;     ...
;                     } else if (j + 1 < NSUB) {
;                         const int pbn = (j + 1) & 1, s0n = ((j + 1) & 1) * 16, tp = tid - 256, t = tp & 15, k0 = 4 * (tp >> 4);
;                         const int ro = (s0n + t) * RS + k0;
;                         const f32x4 e4 = *(const LAS f32x4*)(raw + ro), kk4 = *(const LAS f32x4*)(raw + AS + ro), bb4 = *(const LAS f32x4*)(raw + 2 * AS + ro), kd4 = *(const LAS f32x4*)(raw + 3 * AS + ro), r4 = *(const LAS f32x4*)(raw + 4 * AS + ro), v4 = *(const LAS f32x4*)(raw + 5 * AS + ro);
;     ...
;                         const int pbn = (j + 1) & 1, which = wave - 4;
;                         const LAS bf16_t* Am = D64(pbn, which < 2 ? 0 : 1); const LAS bf16_t* Bm = D64(pbn, (which & 1) ? 2 : 3);
;                         f32x4 a = (f32x4){0.f, 0.f, 0.f, 0.f};
; #pragma unroll
;                         for (int kk = 0; kk < 2; ++kk) a = __builtin_amdgcn_mfma_f32_16x16x32_bf16(FRAG(Am, LD64, 0, kk), FRAG(Bm, LD64, 0, kk), a, 0, 0, 0);
; #pragma unroll
;                         for (int rg = 0; rg < 4; ++rg) { const int t = fq * 4 + rg; const bool keep = which < 2 ? (t > fr) : (t >= fr); a[rg] = keep ? a[rg] : 0.f; }
;                         if (which != 1) {
;                             LAS bf16_t* dst = AMB(pbn, which == 0 ? 0 : (which == 2 ? 1 : 2));
; #pragma unroll
;                             for (int rg = 0; rg < 4; ++rg) { const float nbv = dpp_f<DPP_XOR1>(a[rg]);
;                                 if ((fr & 1) == 0) *(LAS unsigned*)(dst + (fq * 4 + rg) * LD32 + fr) = cvt_pk_bf16(a[rg], nbv); }
.Lp9_p_top:
	s_and_b32 s24, s85, 1
	s_and_b32 s25, s85, 1
	s_cmpk_gt_u32 s85, 0x10d
	s_cbranch_scc1 .Lp9_a1_done
	v_lshl_or_b32 v184, s25, 4, v74
	v_mad_u32_u24 v184, v184, s62, v81
	v_lshl_add_u32 v204, v184, 2, 0
	ds_read_b128 v[184:187], v204
	ds_read_b128 v[188:191], v204 offset:8704
	ds_read_b128 v[192:195], v204 offset:34816
	ds_read_b128 v[196:199], v204 offset:17408
	ds_read_b128 v[200:203], v204 offset:26112
	ds_read_b128 v[204:207], v204 offset:43520
	v_mov_b32_e32 v251, 0x3020706
	v_mov_b32_e32 v252, 0x5040100
	s_mul_i32 s27, s25, 0x2400
	s_mul_i32 s52, s25, 0x3c00
	v_cndmask_b32_e64 v251, v251, v252, s[4:5]
	v_add3_u32 v214, s27, v116, v117
	v_add_u32_e32 v253, s52, v121
	v_add_u32_e32 v252, 0xec00, v214
.Lp9_a1_done:
	s_cmpk_gt_u32 s85, 0x10e
	s_cbranch_scc1 .Lp9_b865p
	s_xor_b32 s74, s24, 1
	s_mul_i32 s54, s74, 0x2400
	s_add_i32 s54, s54, 0
	s_add_i32 s55, s54, s63
	v_lshlrev_b32_e32 v32, 1, v84
	v_add3_u32 v33, s55, v116, v32
	ds_read_b128 v[28:31], v33 offset:60416
	s_add_i32 s54, s54, s66
	v_add3_u32 v40, s54, v116, v32
	ds_read_b128 v[32:35], v33 offset:60480
	ds_read_b128 v[36:39], v40 offset:60416
	ds_read_b128 v[40:43], v40 offset:60480
	s_and_b64 vcc, exec, s[22:23]
	s_mov_b64 s[54:55], -1
	s_waitcnt lgkmcnt(1)
	v_mfma_f32_16x16x32_bf16 v[28:31], v[28:31], v[36:39], 0
	s_waitcnt lgkmcnt(0)
	v_mfma_f32_16x16x32_bf16 v[28:31], v[32:35], v[40:43], v[28:31]
	s_nop 7
	v_cndmask_b32_e64 v28, 0, v28, s[12:13]
	v_cndmask_b32_e64 v29, v29, 0, s[14:15]
	v_cndmask_b32_e64 v30, 0, v30, s[16:17]
	v_cndmask_b32_e64 v31, 0, v31, s[18:19]
	s_cbranch_vccnz .Lp9_b859p
	s_mul_i32 s54, s74, 0x1400
	v_mov_b32_e32 v33, 0
	v_add_u32_e32 v32, s54, v90
	s_nop 0
	v_mov_b32_dpp v33, v28 quad_perm:[1,0,3,2] row_mask:0xf bank_mask:0xf
	s_and_saveexec_b64 s[54:55], s[4:5]
	v_cvt_pk_bf16_f32 v33, v28, v33
	v_add_u32_e32 v34, v32, v108
	ds_write_b32 v34, v33
	s_or_b64 exec, exec, s[54:55]
	v_mov_b32_e32 v33, 0
	v_add_u32_e32 v32, v32, v109
	s_nop 0
	v_mov_b32_dpp v33, v29 quad_perm:[1,0,3,2] row_mask:0xf bank_mask:0xf
	s_and_saveexec_b64 s[54:55], s[4:5]
	v_cvt_pk_bf16_f32 v33, v29, v33
	ds_write_b32 v32, v33
	s_or_b64 exec, exec, s[54:55]
	v_mov_b32_e32 v33, 0
	s_nop 1
	v_mov_b32_dpp v33, v30 quad_perm:[1,0,3,2] row_mask:0xf bank_mask:0xf
	s_and_saveexec_b64 s[54:55], s[4:5]
	v_cvt_pk_bf16_f32 v33, v30, v33
	ds_write_b32 v32, v33 offset:80
	s_or_b64 exec, exec, s[54:55]
	v_mov_b32_e32 v33, 0
	s_nop 1
	v_mov_b32_dpp v33, v31 quad_perm:[1,0,3,2] row_mask:0xf bank_mask:0xf
	s_and_saveexec_b64 s[54:55], s[4:5]
	v_cvt_pk_bf16_f32 v33, v31, v33
	ds_write_b32 v32, v33 offset:160
	s_or_b64 exec, exec, s[54:55]
	s_mov_b64 s[54:55], 0

; #define LAS __attribute__((address_space(3)))
; __global__ void __launch_bounds__(512, 2) fwd_megakernel(Params p) {
;     ...
;                         f32x4 Pt, Pp, iP, PC;
; #pragma unroll
;                         for (int q = 0; q < 4; ++q) { float x = e4[q];
;                             x += dpp_fz<0x111>(x); x += dpp_fz<0x112>(x); x += dpp_fz<0x114>(x); x += dpp_fz<0x118>(x);
;                             const float pt = __expf(-x), sh = dpp_fz<0x111>(pt);
;                             Pt[q] = pt; Pp[q] = (t == 0) ? 1.0f : sh; iP[q] = __builtin_amdgcn_rcpf(pt); PC[q] = iP[q] * __shfl(pt, lane | 15); }
;                         { u32x2 w_;
;                           w_.x = cvt_pk_bf16(-kk4[0] * Pp[0], -kk4[1] * Pp[1]); w_.y = cvt_pk_bf16(-kk4[2] * Pp[2], -kk4[3] * Pp[3]); *(LAS u32x2*)(D64(pbn, 0) + t * LD64 + k0) = w_;
;                           w_.x = cvt_pk_bf16(r4[0] * Pt[0], r4[1] * Pt[1]); w_.y = cvt_pk_bf16(r4[2] * Pt[2], r4[3] * Pt[3]); *(LAS u32x2*)(D64(pbn, 1) + t * LD64 + k0) = w_;
;                           w_.x = cvt_pk_bf16(bb4[0] * iP[0], bb4[1] * iP[1]); w_.y = cvt_pk_bf16(bb4[2] * iP[2], bb4[3] * iP[3]); *(LAS u32x2*)(D64(pbn, 2) + t * LD64 + k0) = w_;
;                           w_.x = cvt_pk_bf16(kd4[0] * iP[0], kd4[1] * iP[1]); w_.y = cvt_pk_bf16(kd4[2] * iP[2], kd4[3] * iP[3]); *(LAS u32x2*)(D64(pbn, 3) + t * LD64 + k0) = w_; }
;                         {
;                             unsigned own[6];
;                             own[0] = cvt_pk_bf16(bb4[0] * PC[0], bb4[1] * PC[1]); own[1] = cvt_pk_bf16(bb4[2] * PC[2], bb4[3] * PC[3]);
;                             own[2] = cvt_pk_bf16(kd4[0] * PC[0], kd4[1] * PC[1]); own[3] = cvt_pk_bf16(kd4[2] * PC[2], kd4[3] * PC[3]);
;                             own[4] = cvt_pk_bf16(v4[0], v4[1]); own[5] = cvt_pk_bf16(v4[2], v4[3]);
;                             const bool ev = (t & 1) == 0;
; #pragma unroll
;                             for (int q = 0; q < 6; ++q) { const unsigned pt = dpp_u<DPP_XOR1>(own[q]);
;                                 const unsigned val = ev ? ((own[q] & 0xffffu) | (pt << 16)) : ((pt >> 16) | (own[q] & 0xffff0000u));
;                                 const int row = k0 + 2 * (q & 1) + (ev ? 0 : 1), col = ev ? t : t - 1;
;                                 *(LAS unsigned*)(D32(pbn, q >> 1) + row * LD32 + col) = val; }
;                         }
.Lp9_b865p:
	s_and_b32 s25, s85, 1
	s_cmpk_gt_u32 s85, 0x10d
	s_cbranch_scc1 .Lp9_a_done
	s_waitcnt lgkmcnt(5)
	v_add_f32_dpp v184, v184, v184 row_shr:1 row_mask:0xf bank_mask:0xf bound_ctrl:1
	v_add_f32_dpp v185, v185, v185 row_shr:1 row_mask:0xf bank_mask:0xf bound_ctrl:1
	v_add_f32_dpp v186, v186, v186 row_shr:1 row_mask:0xf bank_mask:0xf bound_ctrl:1
	v_add_f32_dpp v187, v187, v187 row_shr:1 row_mask:0xf bank_mask:0xf bound_ctrl:1
	v_add_f32_dpp v184, v184, v184 row_shr:2 row_mask:0xf bank_mask:0xf bound_ctrl:1
	v_add_f32_dpp v185, v185, v185 row_shr:2 row_mask:0xf bank_mask:0xf bound_ctrl:1
	v_add_f32_dpp v186, v186, v186 row_shr:2 row_mask:0xf bank_mask:0xf bound_ctrl:1
	v_add_f32_dpp v187, v187, v187 row_shr:2 row_mask:0xf bank_mask:0xf bound_ctrl:1
	v_add_f32_dpp v184, v184, v184 row_shr:4 row_mask:0xf bank_mask:0xf bound_ctrl:1
	v_add_f32_dpp v185, v185, v185 row_shr:4 row_mask:0xf bank_mask:0xf bound_ctrl:1
	v_add_f32_dpp v186, v186, v186 row_shr:4 row_mask:0xf bank_mask:0xf bound_ctrl:1
	v_add_f32_dpp v187, v187, v187 row_shr:4 row_mask:0xf bank_mask:0xf bound_ctrl:1
	v_add_f32_dpp v184, v184, v184 row_shr:8 row_mask:0xf bank_mask:0xf bound_ctrl:1
	v_add_f32_dpp v185, v185, v185 row_shr:8 row_mask:0xf bank_mask:0xf bound_ctrl:1
	v_add_f32_dpp v186, v186, v186 row_shr:8 row_mask:0xf bank_mask:0xf bound_ctrl:1
	v_add_f32_dpp v187, v187, v187 row_shr:8 row_mask:0xf bank_mask:0xf bound_ctrl:1
	v_mul_f32_e32 v184, 0xbfb8aa3b, v184
	v_mul_f32_e32 v185, 0xbfb8aa3b, v185
	v_mul_f32_e32 v186, 0xbfb8aa3b, v186
	v_mul_f32_e32 v187, 0xbfb8aa3b, v187
	v_exp_f32_e32 v184, v184
	v_exp_f32_e32 v185, v185
	v_exp_f32_e32 v186, v186
	v_exp_f32_e32 v187, v187
	v_mov_b32_dpp v208, v184 row_shr:1 row_mask:0xf bank_mask:0xf bound_ctrl:1
	v_mov_b32_dpp v209, v185 row_shr:1 row_mask:0xf bank_mask:0xf bound_ctrl:1
	v_mov_b32_dpp v210, v186 row_shr:1 row_mask:0xf bank_mask:0xf bound_ctrl:1
	v_mov_b32_dpp v211, v187 row_shr:1 row_mask:0xf bank_mask:0xf bound_ctrl:1
	v_mov_b32_dpp v247, v184 row_newbcast:15 row_mask:0xf bank_mask:0xf
	v_mov_b32_dpp v248, v185 row_newbcast:15 row_mask:0xf bank_mask:0xf
	v_mov_b32_dpp v249, v186 row_newbcast:15 row_mask:0xf bank_mask:0xf
	v_mov_b32_dpp v250, v187 row_newbcast:15 row_mask:0xf bank_mask:0xf
	v_rcp_f32_e32 v212, v184
	v_rcp_f32_e32 v213, v185
	v_rcp_f32_e32 v215, v186
	v_rcp_f32_e32 v216, v187
	v_cndmask_b32_e64 v208, v208, 1.0, s[2:3]
	v_cndmask_b32_e64 v209, v209, 1.0, s[2:3]
	v_cndmask_b32_e64 v210, v210, 1.0, s[2:3]
	v_cndmask_b32_e64 v211, v211, 1.0, s[2:3]
	s_waitcnt lgkmcnt(4)
	v_mul_f32_e64 v208, v208, -v188
	v_mul_f32_e64 v209, v209, -v189
	v_mul_f32_e64 v210, v210, -v190
	v_mul_f32_e64 v211, v211, -v191
	v_cvt_pk_bf16_f32 v188, v208, v209
	v_cvt_pk_bf16_f32 v189, v210, v211
	ds_write_b64 v214, v[188:189] offset:60416
	s_waitcnt lgkmcnt(4)
	v_mul_f32_e32 v192, v192, v184
	v_mul_f32_e32 v193, v193, v185
	v_mul_f32_e32 v194, v194, v186
	v_mul_f32_e32 v195, v195, v187
	v_cvt_pk_bf16_f32 v190, v192, v193
	v_cvt_pk_bf16_f32 v191, v194, v195
	ds_write_b64 v214, v[190:191] offset:62720
	s_waitcnt lgkmcnt(4)
	v_mul_f32_e32 v208, v196, v212
	v_mul_f32_e32 v209, v197, v213
	v_mul_f32_e32 v210, v198, v215
	v_mul_f32_e32 v211, v199, v216
	v_cvt_pk_bf16_f32 v188, v208, v209
	v_cvt_pk_bf16_f32 v189, v210, v211
	ds_write_b64 v214, v[188:189] offset:65024
	s_waitcnt lgkmcnt(4)
	v_mul_f32_e32 v208, v200, v212
	v_mul_f32_e32 v209, v201, v213
	v_mul_f32_e32 v210, v202, v215
	v_mul_f32_e32 v211, v203, v216
	v_cvt_pk_bf16_f32 v190, v208, v209
	v_cvt_pk_bf16_f32 v191, v210, v211
	ds_write_b64 v252, v[190:191] offset:6912
	v_mul_f32_e32 v247, v212, v247
	v_mul_f32_e32 v248, v213, v248
	v_mul_f32_e32 v249, v215, v249
	v_mul_f32_e32 v250, v216, v250
	v_mul_f32_e32 v196, v196, v247
	v_mul_f32_e32 v197, v197, v248
	v_mul_f32_e32 v198, v198, v249
	v_mul_f32_e32 v199, v199, v250
	v_mul_f32_e32 v200, v200, v247
	v_mul_f32_e32 v201, v201, v248
	v_mul_f32_e32 v202, v202, v249
	v_mul_f32_e32 v203, v203, v250
	v_cvt_pk_bf16_f32 v208, v196, v197
	v_cvt_pk_bf16_f32 v209, v198, v199
	v_cvt_pk_bf16_f32 v210, v200, v201
	v_cvt_pk_bf16_f32 v211, v202, v203
	s_waitcnt lgkmcnt(4)
	v_cvt_pk_bf16_f32 v212, v204, v205
	v_cvt_pk_bf16_f32 v213, v206, v207
	v_mov_b32_dpp v196, v208 quad_perm:[1,0,3,2] row_mask:0xf bank_mask:0xf
	v_mov_b32_dpp v197, v209 quad_perm:[1,0,3,2] row_mask:0xf bank_mask:0xf
	v_mov_b32_dpp v198, v210 quad_perm:[1,0,3,2] row_mask:0xf bank_mask:0xf
	v_mov_b32_dpp v199, v211 quad_perm:[1,0,3,2] row_mask:0xf bank_mask:0xf
	v_mov_b32_dpp v200, v212 quad_perm:[1,0,3,2] row_mask:0xf bank_mask:0xf
	v_mov_b32_dpp v201, v213 quad_perm:[1,0,3,2] row_mask:0xf bank_mask:0xf
	v_perm_b32 v196, v196, v208, v251
	v_perm_b32 v197, v197, v209, v251
	v_perm_b32 v198, v198, v210, v251
	v_perm_b32 v199, v199, v211, v251
	v_perm_b32 v200, v200, v212, v251
	v_perm_b32 v201, v201, v213, v251
	ds_write_b32 v253, v196
	ds_write_b32 v253, v197 offset:160
	ds_write_b32 v253, v198 offset:5120
	ds_write_b32 v253, v199 offset:5280
	ds_write_b32 v253, v200 offset:10240
	ds_write_b32 v253, v201 offset:10400
	s_and_saveexec_b64 s[52:53], s[6:7]
	v_lshl_add_u32 v204, s25, 8, v83
	ds_write_b128 v204, v[184:187]
	s_or_b64 exec, exec, s[52:53]
